# v17 + P1 K-loop closing barrier moved to the back edge; exit barrier only for the leading half (replaces ALIGN barrier): leader starts epilogue one MFMA block earlier
# speedup vs baseline: 1.0047x; 1.0047x over previous
; #define PG8_STAGE(bufoff, gbase, voff) do { _Pragma("unroll") for (int _i = 0; _i < 2; ++_i) \
;         __builtin_amdgcn_global_load_lds((const unsigned*)((const char*)(gbase) + (voff)[_i]), (PG8_LAS unsigned*)(lds + (bufoff) + ldsw + _i * 8192), 16, 0, 0); } while (0)
; #define PG8_LDA(dst, b, h) do { _Pragma("unroll") for (int m = 0; m < 4; ++m) _Pragma("unroll") for (int k = 0; k < 2; ++k) dst[m][k] = *(const PG8_LAS bf16x8*)(lds + PG8_SA(b, h) + aoff + m * 2048 + k * 1024); } while (0)
; #define PG8_LDB(dst, b, h) do { _Pragma("unroll") for (int n = 0; n < 2; ++n) _Pragma("unroll") for (int k = 0; k < 2; ++k) dst[n][k] = *(const PG8_LAS bf16x8*)(lds + PG8_SB(b, h) + boff + n * 2048 + k * 1024); } while (0)
; #define PG8_MMA(ai, bj, At, Bt) do { __builtin_amdgcn_s_setprio(1); _Pragma("unroll") for (int m = 0; m < 4; ++m) _Pragma("unroll") for (int n = 0; n < 2; ++n) _Pragma("unroll") for (int k = 0; k < 2; ++k) \
;         acc[ai][bj][m][n] = __builtin_amdgcn_mfma_f32_16x16x32_bf16(Bt[n][k], At[m][k], acc[ai][bj][m][n], 0, 0, 0); __builtin_amdgcn_s_setprio(0); } while (0)
; #define PG8_WAIT_V(n) asm volatile("s_waitcnt vmcnt(" #n ")" ::: "memory")
; #define PG8_BAR __builtin_amdgcn_s_barrier()
; template <class Epi, class Sched, bool ALIGN_EPI = false, bool SP2 = false>
; __device__ __forceinline__ void gemm_phase(PG8_LAS unsigned char* lds, const Gemm g, const Sched& S, const Epi& E) {
;     ...
;         for (int t = 0; t < nt; t += 2) {
;             const bool last = (t == nt - 2);
;             const char* a1 = cA + (size_t)(t + 1) * kstep;
;             const char* a2 = last ? nA : cA + (size_t)(t + 2) * kstep; const char* b2 = last ? nB : cB + (size_t)(t + 2) * kstep;
;             const char* a3 = a2 + kstep; const char* b3 = b2 + kstep;
;             if (last && has_next) S.a_ready(nxt);
;             if constexpr (SP2) {
;             PG8_LDB(B0, 0, 0); PG8_LDB(B1, 0, 1); PG8_SCHED; PG8_LDA(At, 0, 0); PG8_STAGE(PG8_SA(1, 1), a1 + hstep, voffA);
;             PG8_WAIT_V(8); PG8_WAIT_L(0); PG8_BAR; PG8_MMA(0, 0, At, B0); PG8_MMA(0, 1, At, B1); PG8_BAR; PG8_SCHED;
;             PG8_LDA(At, 0, 1); PG8_STAGE(PG8_SB(0, 0), b2, voffB); PG8_STAGE(PG8_SB(0, 1), b2 + hstep, voffB); PG8_STAGE(PG8_SA(0, 0), a2, voffA);
;             PG8_WAIT_V(8); PG8_WAIT_L(0); PG8_BAR; PG8_MMA(1, 0, At, B0); PG8_MMA(1, 1, At, B1); PG8_BAR; PG8_SCHED;
.LBB0_162:
	ds_read_b128 v[130:133], v183
	ds_read_b128 v[134:137], v183 offset:1024
	ds_read_b128 v[138:141], v183 offset:2048
	ds_read_b128 v[142:145], v183 offset:3072
	ds_read_b128 v[172:175], v184
	ds_read_b128 v[176:179], v184 offset:1024
	ds_read_b128 v[192:195], v184 offset:2048
	ds_read_b128 v[196:199], v184 offset:3072
	s_add_u32 s50, s48, 0xfffc0080
	s_addc_u32 s51, s49, -1
	s_cmp_eq_u32 s93, 12
	s_cselect_b32 s65, s5, s51
	s_cselect_b32 s64, s34, s50
	s_cselect_b32 s51, s27, s92
	s_cselect_b32 s50, s35, s41
	v_lshl_add_u64 v[232:233], s[48:49], 0, v[164:165]
	s_add_i32 m0, s47, 0xc000
	ds_read_b128 v[200:203], v185
	ds_read_b128 v[204:207], v185 offset:1024
	ds_read_b128 v[208:211], v185 offset:2048
	ds_read_b128 v[212:215], v185 offset:3072
	ds_read_b128 v[216:219], v185 offset:4096
	ds_read_b128 v[220:223], v185 offset:5120
	ds_read_b128 v[224:227], v185 offset:6144
	ds_read_b128 v[228:231], v185 offset:7168
	global_load_lds_dwordx4 v[232:233], off
	v_lshl_add_u64 v[232:233], s[48:49], 0, v[166:167]
	s_add_i32 m0, s47, 0xe000
	s_nop 0
	global_load_lds_dwordx4 v[232:233], off
	s_waitcnt vmcnt(8)
	s_waitcnt lgkmcnt(0)
	s_barrier
	s_setprio 1
	s_waitcnt lgkmcnt(0)
	v_mfma_f32_16x16x32_bf16 v[126:129], v[130:133], v[200:203], v[126:129]
	v_mfma_f32_16x16x32_bf16 v[122:125], v[138:141], v[200:203], v[122:125]
	v_mfma_f32_16x16x32_bf16 v[110:113], v[130:133], v[208:211], v[110:113]
	v_mfma_f32_16x16x32_bf16 v[106:109], v[138:141], v[208:211], v[106:109]
	v_mfma_f32_16x16x32_bf16 v[94:97], v[130:133], v[216:219], v[94:97]
	v_mfma_f32_16x16x32_bf16 v[90:93], v[138:141], v[216:219], v[90:93]
	v_mfma_f32_16x16x32_bf16 v[78:81], v[130:133], v[224:227], v[78:81]
	v_mfma_f32_16x16x32_bf16 v[74:77], v[138:141], v[224:227], v[74:77]
	v_mfma_f32_16x16x32_bf16 v[126:129], v[134:137], v[204:207], v[126:129]
	v_mfma_f32_16x16x32_bf16 v[122:125], v[142:145], v[204:207], v[122:125]
	v_mfma_f32_16x16x32_bf16 v[110:113], v[134:137], v[212:215], v[110:113]
	v_mfma_f32_16x16x32_bf16 v[106:109], v[142:145], v[212:215], v[106:109]
	v_mfma_f32_16x16x32_bf16 v[94:97], v[134:137], v[220:223], v[94:97]
	v_mfma_f32_16x16x32_bf16 v[90:93], v[142:145], v[220:223], v[90:93]
	v_mfma_f32_16x16x32_bf16 v[78:81], v[134:137], v[228:231], v[78:81]
	v_mfma_f32_16x16x32_bf16 v[74:77], v[142:145], v[228:231], v[74:77]
	s_setprio 0
	s_setprio 1
	v_mfma_f32_16x16x32_bf16 v[118:121], v[172:175], v[200:203], v[118:121]
	v_mfma_f32_16x16x32_bf16 v[114:117], v[192:195], v[200:203], v[114:117]
	v_mfma_f32_16x16x32_bf16 v[102:105], v[172:175], v[208:211], v[102:105]
	v_mfma_f32_16x16x32_bf16 v[98:101], v[192:195], v[208:211], v[98:101]
	v_mfma_f32_16x16x32_bf16 v[86:89], v[172:175], v[216:219], v[86:89]
	v_mfma_f32_16x16x32_bf16 v[82:85], v[192:195], v[216:219], v[82:85]
	v_mfma_f32_16x16x32_bf16 v[70:73], v[172:175], v[224:227], v[70:73]
	v_mfma_f32_16x16x32_bf16 v[66:69], v[192:195], v[224:227], v[66:69]
	v_mfma_f32_16x16x32_bf16 v[118:121], v[176:179], v[204:207], v[118:121]
	v_mfma_f32_16x16x32_bf16 v[114:117], v[196:199], v[204:207], v[114:117]
	v_mfma_f32_16x16x32_bf16 v[102:105], v[176:179], v[212:215], v[102:105]
	v_mfma_f32_16x16x32_bf16 v[98:101], v[196:199], v[212:215], v[98:101]
	v_mfma_f32_16x16x32_bf16 v[86:89], v[176:179], v[220:223], v[86:89]
	v_mfma_f32_16x16x32_bf16 v[82:85], v[196:199], v[220:223], v[82:85]
	v_mfma_f32_16x16x32_bf16 v[70:73], v[176:179], v[228:231], v[70:73]
	v_mfma_f32_16x16x32_bf16 v[66:69], v[196:199], v[228:231], v[66:69]
	s_setprio 0
	s_barrier
	s_add_i32 s94, s85, s72
	v_lshl_add_u64 v[232:233], s[50:51], 0, v[148:149]
	s_mov_b32 m0, s94
	ds_read_b128 v[200:203], v185 offset:16384
	ds_read_b128 v[204:207], v185 offset:17408
	ds_read_b128 v[208:211], v185 offset:18432
	ds_read_b128 v[212:215], v185 offset:19456
	ds_read_b128 v[216:219], v185 offset:20480
	ds_read_b128 v[220:223], v185 offset:21504
	ds_read_b128 v[224:227], v185 offset:22528
	ds_read_b128 v[228:231], v185 offset:23552
	global_load_lds_dwordx4 v[232:233], off
	s_add_i32 m0, s94, 0x2000
	s_add_u32 s94, s50, 0x40000
	v_lshl_add_u64 v[234:235], s[50:51], 0, v[152:153]
	s_addc_u32 s95, s51, 0
	s_add_i32 s96, s86, s72
	global_load_lds_dwordx4 v[234:235], off
	v_lshl_add_u64 v[236:237], s[94:95], 0, v[148:149]
	s_mov_b32 m0, s96
	v_lshl_add_u64 v[238:239], s[64:65], 0, v[150:151]
	global_load_lds_dwordx4 v[236:237], off
	v_lshl_add_u64 v[236:237], s[94:95], 0, v[152:153]
	s_add_i32 m0, s96, 0x2000
	s_nop 0
	global_load_lds_dwordx4 v[236:237], off
	v_lshl_add_u64 v[236:237], s[64:65], 0, v[146:147]
	s_mov_b32 m0, s47
	s_nop 0
	global_load_lds_dwordx4 v[236:237], off
	s_mov_b32 m0, s73
	s_nop 0
	global_load_lds_dwordx4 v[238:239], off
	s_waitcnt vmcnt(8)
	s_waitcnt lgkmcnt(0)
	s_barrier
; #define PG8_STAGE(bufoff, gbase, voff) do { _Pragma("unroll") for (int _i = 0; _i < 2; ++_i) \
;         __builtin_amdgcn_global_load_lds((const unsigned*)((const char*)(gbase) + (voff)[_i]), (PG8_LAS unsigned*)(lds + (bufoff) + ldsw + _i * 8192), 16, 0, 0); } while (0)
; #define PG8_LDA(dst, b, h) do { _Pragma("unroll") for (int m = 0; m < 4; ++m) _Pragma("unroll") for (int k = 0; k < 2; ++k) dst[m][k] = *(const PG8_LAS bf16x8*)(lds + PG8_SA(b, h) + aoff + m * 2048 + k * 1024); } while (0)
; #define PG8_LDB(dst, b, h) do { _Pragma("unroll") for (int n = 0; n < 2; ++n) _Pragma("unroll") for (int k = 0; k < 2; ++k) dst[n][k] = *(const PG8_LAS bf16x8*)(lds + PG8_SB(b, h) + boff + n * 2048 + k * 1024); } while (0)
; #define PG8_MMA(ai, bj, At, Bt) do { __builtin_amdgcn_s_setprio(1); _Pragma("unroll") for (int m = 0; m < 4; ++m) _Pragma("unroll") for (int n = 0; n < 2; ++n) _Pragma("unroll") for (int k = 0; k < 2; ++k) \
;         acc[ai][bj][m][n] = __builtin_amdgcn_mfma_f32_16x16x32_bf16(Bt[n][k], At[m][k], acc[ai][bj][m][n], 0, 0, 0); __builtin_amdgcn_s_setprio(0); } while (0)
; #define PG8_WAIT_V(n) asm volatile("s_waitcnt vmcnt(" #n ")" ::: "memory")
; #define PG8_WAIT_L(n) asm volatile("s_waitcnt lgkmcnt(" #n ")" ::: "memory")
; #define PG8_BAR __builtin_amdgcn_s_barrier()
; #define PG8_SCHED __builtin_amdgcn_sched_barrier(0)
; template <class Epi, class Sched, bool ALIGN_EPI = false, bool SP2 = false>
; __device__ __forceinline__ void gemm_phase(PG8_LAS unsigned char* lds, const Gemm g, const Sched& S, const Epi& E) {
;     ...
;             PG8_WAIT_V(8); PG8_WAIT_L(0); PG8_BAR; PG8_MMA(1, 0, At, B0); PG8_MMA(1, 1, At, B1); PG8_BAR; PG8_SCHED;
;             PG8_LDB(B0, 1, 0); PG8_LDB(B1, 1, 1); PG8_SCHED; PG8_LDA(At, 1, 0); PG8_STAGE(PG8_SA(0, 1), a2 + hstep, voffA);
;             PG8_WAIT_V(8); PG8_WAIT_L(0); PG8_BAR; PG8_MMA(0, 0, At, B0); PG8_MMA(0, 1, At, B1); PG8_BAR; PG8_SCHED;
	s_setprio 1
	s_waitcnt lgkmcnt(0)
	v_mfma_f32_16x16x32_bf16 v[62:65], v[130:133], v[200:203], v[62:65]
	v_mfma_f32_16x16x32_bf16 v[58:61], v[138:141], v[200:203], v[58:61]
	v_mfma_f32_16x16x32_bf16 v[46:49], v[130:133], v[208:211], v[46:49]
	v_mfma_f32_16x16x32_bf16 v[42:45], v[138:141], v[208:211], v[42:45]
	v_mfma_f32_16x16x32_bf16 v[30:33], v[130:133], v[216:219], v[30:33]
	v_mfma_f32_16x16x32_bf16 v[26:29], v[138:141], v[216:219], v[26:29]
	v_mfma_f32_16x16x32_bf16 v[14:17], v[130:133], v[224:227], v[14:17]
	v_mfma_f32_16x16x32_bf16 v[10:13], v[138:141], v[224:227], v[10:13]
	v_mfma_f32_16x16x32_bf16 v[62:65], v[134:137], v[204:207], v[62:65]
	v_mfma_f32_16x16x32_bf16 v[58:61], v[142:145], v[204:207], v[58:61]
	v_mfma_f32_16x16x32_bf16 v[46:49], v[134:137], v[212:215], v[46:49]
	v_mfma_f32_16x16x32_bf16 v[42:45], v[142:145], v[212:215], v[42:45]
	v_mfma_f32_16x16x32_bf16 v[30:33], v[134:137], v[220:223], v[30:33]
	v_mfma_f32_16x16x32_bf16 v[26:29], v[142:145], v[220:223], v[26:29]
	v_mfma_f32_16x16x32_bf16 v[14:17], v[134:137], v[228:231], v[14:17]
	v_mfma_f32_16x16x32_bf16 v[10:13], v[142:145], v[228:231], v[10:13]
	s_setprio 0
	s_setprio 1
	v_mfma_f32_16x16x32_bf16 v[54:57], v[172:175], v[200:203], v[54:57]
	v_mfma_f32_16x16x32_bf16 v[50:53], v[192:195], v[200:203], v[50:53]
	v_mfma_f32_16x16x32_bf16 v[38:41], v[172:175], v[208:211], v[38:41]
	v_mfma_f32_16x16x32_bf16 v[34:37], v[192:195], v[208:211], v[34:37]
	v_mfma_f32_16x16x32_bf16 v[22:25], v[172:175], v[216:219], v[22:25]
	v_mfma_f32_16x16x32_bf16 v[18:21], v[192:195], v[216:219], v[18:21]
	v_mfma_f32_16x16x32_bf16 v[6:9], v[172:175], v[224:227], v[6:9]
	v_mfma_f32_16x16x32_bf16 v[2:5], v[192:195], v[224:227], v[2:5]
	v_mfma_f32_16x16x32_bf16 v[54:57], v[176:179], v[204:207], v[54:57]
	v_mfma_f32_16x16x32_bf16 v[50:53], v[196:199], v[204:207], v[50:53]
	v_mfma_f32_16x16x32_bf16 v[38:41], v[176:179], v[212:215], v[38:41]
	v_mfma_f32_16x16x32_bf16 v[34:37], v[196:199], v[212:215], v[34:37]
	v_mfma_f32_16x16x32_bf16 v[22:25], v[176:179], v[220:223], v[22:25]
	v_mfma_f32_16x16x32_bf16 v[18:21], v[196:199], v[220:223], v[18:21]
	v_mfma_f32_16x16x32_bf16 v[6:9], v[176:179], v[228:231], v[6:9]
	v_mfma_f32_16x16x32_bf16 v[2:5], v[196:199], v[228:231], v[2:5]
	s_setprio 0
	s_barrier
	s_add_i32 s94, 0, 0x18000
	s_add_i32 s95, 0, 0x1c000
	v_add_u32_e32 v142, s94, v181
	v_add_u32_e32 v154, s95, v181
	ds_read_b128 v[130:133], v142
	ds_read_b128 v[134:137], v142 offset:1024
	ds_read_b128 v[138:141], v142 offset:2048
	ds_read_b128 v[142:145], v142 offset:3072
	ds_read_b128 v[172:175], v154
	ds_read_b128 v[176:179], v154 offset:1024
	ds_read_b128 v[192:195], v154 offset:2048
	ds_read_b128 v[196:199], v154 offset:3072
	s_add_u32 s64, s64, 0x40000
	s_addc_u32 s65, s65, 0
	s_mov_b32 m0, s74
	v_lshl_add_u64 v[240:241], s[64:65], 0, v[146:147]
	ds_read_b128 v[200:203], v185 offset:32768
	ds_read_b128 v[204:207], v185 offset:33792
	ds_read_b128 v[208:211], v185 offset:34816
	ds_read_b128 v[212:215], v185 offset:35840
	ds_read_b128 v[216:219], v185 offset:36864
	ds_read_b128 v[220:223], v185 offset:37888
	ds_read_b128 v[224:227], v185 offset:38912
	ds_read_b128 v[228:231], v185 offset:39936
	global_load_lds_dwordx4 v[240:241], off
	v_lshl_add_u64 v[240:241], s[64:65], 0, v[150:151]
	s_mov_b32 m0, s75
	s_nop 0
	global_load_lds_dwordx4 v[240:241], off
	s_waitcnt vmcnt(8)
	s_waitcnt lgkmcnt(0)
	s_barrier
	s_setprio 1
	s_waitcnt lgkmcnt(0)
	v_mfma_f32_16x16x32_bf16 v[126:129], v[130:133], v[200:203], v[126:129]
	v_mfma_f32_16x16x32_bf16 v[122:125], v[138:141], v[200:203], v[122:125]
	v_mfma_f32_16x16x32_bf16 v[110:113], v[130:133], v[208:211], v[110:113]
	v_mfma_f32_16x16x32_bf16 v[106:109], v[138:141], v[208:211], v[106:109]
	v_mfma_f32_16x16x32_bf16 v[94:97], v[130:133], v[216:219], v[94:97]
	v_mfma_f32_16x16x32_bf16 v[90:93], v[138:141], v[216:219], v[90:93]
	v_mfma_f32_16x16x32_bf16 v[78:81], v[130:133], v[224:227], v[78:81]
	v_mfma_f32_16x16x32_bf16 v[74:77], v[138:141], v[224:227], v[74:77]
	v_mfma_f32_16x16x32_bf16 v[126:129], v[134:137], v[204:207], v[126:129]
	v_mfma_f32_16x16x32_bf16 v[122:125], v[142:145], v[204:207], v[122:125]
	v_mfma_f32_16x16x32_bf16 v[110:113], v[134:137], v[212:215], v[110:113]
	v_mfma_f32_16x16x32_bf16 v[106:109], v[142:145], v[212:215], v[106:109]
	v_mfma_f32_16x16x32_bf16 v[94:97], v[134:137], v[220:223], v[94:97]
	v_mfma_f32_16x16x32_bf16 v[90:93], v[142:145], v[220:223], v[90:93]
	v_mfma_f32_16x16x32_bf16 v[78:81], v[134:137], v[228:231], v[78:81]
	v_mfma_f32_16x16x32_bf16 v[74:77], v[142:145], v[228:231], v[74:77]
	s_setprio 0
	s_setprio 1
	v_mfma_f32_16x16x32_bf16 v[118:121], v[172:175], v[200:203], v[118:121]
	v_mfma_f32_16x16x32_bf16 v[114:117], v[192:195], v[200:203], v[114:117]
	v_mfma_f32_16x16x32_bf16 v[102:105], v[172:175], v[208:211], v[102:105]
	v_mfma_f32_16x16x32_bf16 v[98:101], v[192:195], v[208:211], v[98:101]
	v_mfma_f32_16x16x32_bf16 v[86:89], v[172:175], v[216:219], v[86:89]
	v_mfma_f32_16x16x32_bf16 v[82:85], v[192:195], v[216:219], v[82:85]
	v_mfma_f32_16x16x32_bf16 v[70:73], v[172:175], v[224:227], v[70:73]
	v_mfma_f32_16x16x32_bf16 v[66:69], v[192:195], v[224:227], v[66:69]
	v_mfma_f32_16x16x32_bf16 v[118:121], v[176:179], v[204:207], v[118:121]
	v_mfma_f32_16x16x32_bf16 v[114:117], v[196:199], v[204:207], v[114:117]
	v_mfma_f32_16x16x32_bf16 v[102:105], v[176:179], v[212:215], v[102:105]
	v_mfma_f32_16x16x32_bf16 v[98:101], v[196:199], v[212:215], v[98:101]
	v_mfma_f32_16x16x32_bf16 v[86:89], v[176:179], v[220:223], v[86:89]
	v_mfma_f32_16x16x32_bf16 v[82:85], v[196:199], v[220:223], v[82:85]
	v_mfma_f32_16x16x32_bf16 v[70:73], v[176:179], v[228:231], v[70:73]
	v_mfma_f32_16x16x32_bf16 v[66:69], v[196:199], v[228:231], v[66:69]
	s_setprio 0
	s_barrier
; #define PG8_STAGE(bufoff, gbase, voff) do { _Pragma("unroll") for (int _i = 0; _i < 2; ++_i) \
;         __builtin_amdgcn_global_load_lds((const unsigned*)((const char*)(gbase) + (voff)[_i]), (PG8_LAS unsigned*)(lds + (bufoff) + ldsw + _i * 8192), 16, 0, 0); } while (0)
; #define PG8_LDA(dst, b, h) do { _Pragma("unroll") for (int m = 0; m < 4; ++m) _Pragma("unroll") for (int k = 0; k < 2; ++k) dst[m][k] = *(const PG8_LAS bf16x8*)(lds + PG8_SA(b, h) + aoff + m * 2048 + k * 1024); } while (0)
; #define PG8_MMA(ai, bj, At, Bt) do { __builtin_amdgcn_s_setprio(1); _Pragma("unroll") for (int m = 0; m < 4; ++m) _Pragma("unroll") for (int n = 0; n < 2; ++n) _Pragma("unroll") for (int k = 0; k < 2; ++k) \
;         acc[ai][bj][m][n] = __builtin_amdgcn_mfma_f32_16x16x32_bf16(Bt[n][k], At[m][k], acc[ai][bj][m][n], 0, 0, 0); __builtin_amdgcn_s_setprio(0); } while (0)
; #define PG8_WAIT_V(n) asm volatile("s_waitcnt vmcnt(" #n ")" ::: "memory")
; #define PG8_WAIT_L(n) asm volatile("s_waitcnt lgkmcnt(" #n ")" ::: "memory")
; #define PG8_BAR __builtin_amdgcn_s_barrier()
; #define PG8_SCHED __builtin_amdgcn_sched_barrier(0)
; template <class Epi, class Sched, bool ALIGN_EPI = false, bool SP2 = false>
; __device__ __forceinline__ void gemm_phase(PG8_LAS unsigned char* lds, const Gemm g, const Sched& S, const Epi& E) {
;     ...
;             PG8_LDA(At, 1, 1); PG8_STAGE(PG8_SB(1, 0), b3, voffB); PG8_STAGE(PG8_SB(1, 1), b3 + hstep, voffB); PG8_STAGE(PG8_SA(1, 0), a3, voffA);
;             PG8_WAIT_V(8); PG8_WAIT_L(0); PG8_BAR; PG8_MMA(1, 0, At, B0); PG8_MMA(1, 1, At, B1); PG8_BAR; PG8_SCHED;
;     ...
;         if constexpr (ALIGN_EPI) { if (wr == 0) PG8_BAR; }
	s_add_i32 s64, s94, s72
	v_lshl_add_u64 v[232:233], v[232:233], 0, s[12:13]
	s_mov_b32 m0, s64
	ds_read_b128 v[200:203], v185 offset:49152
	ds_read_b128 v[204:207], v185 offset:50176
	ds_read_b128 v[208:211], v185 offset:51200
	ds_read_b128 v[212:215], v185 offset:52224
	ds_read_b128 v[216:219], v185 offset:53248
	ds_read_b128 v[220:223], v185 offset:54272
	ds_read_b128 v[224:227], v185 offset:55296
	ds_read_b128 v[228:231], v185 offset:56320
	global_load_lds_dwordx4 v[232:233], off
	s_add_i32 m0, s64, 0x2000
	s_add_u32 s50, s50, 0x40080
	v_lshl_add_u64 v[232:233], v[234:235], 0, s[12:13]
	s_addc_u32 s51, s51, 0
	s_add_i32 s64, s95, s72
	global_load_lds_dwordx4 v[232:233], off
	v_lshl_add_u64 v[232:233], s[50:51], 0, v[148:149]
	s_mov_b32 m0, s64
	s_nop 0
	global_load_lds_dwordx4 v[232:233], off
	v_lshl_add_u64 v[232:233], s[50:51], 0, v[152:153]
	s_add_i32 m0, s64, 0x2000
	s_nop 0
	global_load_lds_dwordx4 v[232:233], off
	v_lshl_add_u64 v[232:233], v[236:237], 0, s[12:13]
	s_mov_b32 m0, s82
	s_nop 0
	global_load_lds_dwordx4 v[232:233], off
	v_lshl_add_u64 v[232:233], v[238:239], 0, s[12:13]
	s_mov_b32 m0, s83
	s_nop 0
	global_load_lds_dwordx4 v[232:233], off
	s_waitcnt vmcnt(8)
	s_waitcnt lgkmcnt(0)
	s_barrier
	s_setprio 1
	s_waitcnt lgkmcnt(0)
	v_mfma_f32_16x16x32_bf16 v[62:65], v[130:133], v[200:203], v[62:65]
	v_mfma_f32_16x16x32_bf16 v[58:61], v[138:141], v[200:203], v[58:61]
	v_mfma_f32_16x16x32_bf16 v[46:49], v[130:133], v[208:211], v[46:49]
	v_mfma_f32_16x16x32_bf16 v[42:45], v[138:141], v[208:211], v[42:45]
	v_mfma_f32_16x16x32_bf16 v[30:33], v[130:133], v[216:219], v[30:33]
	v_mfma_f32_16x16x32_bf16 v[26:29], v[138:141], v[216:219], v[26:29]
	v_mfma_f32_16x16x32_bf16 v[14:17], v[130:133], v[224:227], v[14:17]
	v_mfma_f32_16x16x32_bf16 v[10:13], v[138:141], v[224:227], v[10:13]
	v_mfma_f32_16x16x32_bf16 v[62:65], v[134:137], v[204:207], v[62:65]
	v_mfma_f32_16x16x32_bf16 v[58:61], v[142:145], v[204:207], v[58:61]
	v_mfma_f32_16x16x32_bf16 v[46:49], v[134:137], v[212:215], v[46:49]
	v_mfma_f32_16x16x32_bf16 v[42:45], v[142:145], v[212:215], v[42:45]
	v_mfma_f32_16x16x32_bf16 v[30:33], v[134:137], v[220:223], v[30:33]
	v_mfma_f32_16x16x32_bf16 v[26:29], v[142:145], v[220:223], v[26:29]
	v_mfma_f32_16x16x32_bf16 v[14:17], v[134:137], v[228:231], v[14:17]
	v_mfma_f32_16x16x32_bf16 v[10:13], v[142:145], v[228:231], v[10:13]
	s_setprio 0
	s_setprio 1
	v_mfma_f32_16x16x32_bf16 v[54:57], v[172:175], v[200:203], v[54:57]
	v_mfma_f32_16x16x32_bf16 v[50:53], v[192:195], v[200:203], v[50:53]
	v_mfma_f32_16x16x32_bf16 v[38:41], v[172:175], v[208:211], v[38:41]
	v_mfma_f32_16x16x32_bf16 v[34:37], v[192:195], v[208:211], v[34:37]
	v_mfma_f32_16x16x32_bf16 v[22:25], v[172:175], v[216:219], v[22:25]
	v_mfma_f32_16x16x32_bf16 v[18:21], v[192:195], v[216:219], v[18:21]
	v_mfma_f32_16x16x32_bf16 v[6:9], v[172:175], v[224:227], v[6:9]
	v_mfma_f32_16x16x32_bf16 v[2:5], v[192:195], v[224:227], v[2:5]
	v_mfma_f32_16x16x32_bf16 v[54:57], v[176:179], v[204:207], v[54:57]
	v_mfma_f32_16x16x32_bf16 v[50:53], v[196:199], v[204:207], v[50:53]
	v_mfma_f32_16x16x32_bf16 v[38:41], v[176:179], v[212:215], v[38:41]
	v_mfma_f32_16x16x32_bf16 v[34:37], v[196:199], v[212:215], v[34:37]
	v_mfma_f32_16x16x32_bf16 v[22:25], v[176:179], v[220:223], v[22:25]
	v_mfma_f32_16x16x32_bf16 v[18:21], v[196:199], v[220:223], v[18:21]
	v_mfma_f32_16x16x32_bf16 v[6:9], v[176:179], v[228:231], v[6:9]
	v_mfma_f32_16x16x32_bf16 v[2:5], v[196:199], v[228:231], v[2:5]
	s_setprio 0
	s_add_i32 s93, s93, 2
	s_add_u32 s48, s48, 0x100
	s_addc_u32 s49, s49, 0
	s_add_u32 s41, s41, 0x100
	s_addc_u32 s92, s92, 0
	s_cmp_gt_u32 s93, 13
	s_cbranch_scc1 .Lp1_kexit
	s_barrier
	s_branch .LBB0_162
.Lp1_kexit:
	s_and_b64 vcc, exec, s[14:15]
	s_cbranch_vccz .LBB0_165
	s_barrier
.LBB0_165:
	s_add_u32 s94, s34, 0x40080
	s_addc_u32 s95, s5, 0
	v_lshl_add_u64 v[232:233], s[94:95], 0, v[164:165]
	s_add_i32 m0, s47, 0xc000
	v_lshl_add_u64 v[234:235], s[94:95], 0, v[166:167]
	global_load_lds_dwordx4 v[232:233], off
	s_add_i32 m0, s47, 0xe000
	s_nop 0
	global_load_lds_dwordx4 v[234:235], off
	s_ashr_i32 s41, s46, 1
	s_and_b32 s27, s46, 1
	s_mul_i32 s34, s41, 0x5000000
	s_mul_hi_i32 s5, s41, 0x5000000
	s_add_u32 s48, s78, s34
	s_addc_u32 s49, s79, s5
	v_lshl_add_u32 v172, s4, 8, v1
	s_cmp_gt_i32 s41, 1
	s_mov_b64 s[4:5], -1
	s_cbranch_scc1 .LBB0_168
	s_andn2_b64 vcc, exec, s[4:5]
	s_cbranch_vccz .LBB0_205
